# v058 + static-stabiliser attention loop with 4-slot LDS ring addressed by immediates (unrolled 4 steps, no per-step LDS base adds) and scalar-base K/V prefetch loads (no 64-bit VALU address math)
# speedup vs baseline: 1.0070x; 1.0070x over previous
.LBB0_496:
	v_ashrrev_i32_e32 v191, 31, v190
	v_lshlrev_b32_e32 v207, 2, v168
	s_waitcnt lgkmcnt(7)
	v_mfma_f32_32x32x16_bf16 v[66:81], v[162:165], v[130:133], v[34:49]
	v_exp_f32_e32 v65, v98
	v_exp_f32_e32 v162, v99
	s_nop 0
	v_cvt_pk_bf16_f32 v98, v65, v162
	v_add_f32_e32 v65, 0, v65
	v_add_f32_e32 v65, v162, v65
	s_waitcnt lgkmcnt(5)
	v_mfma_f32_32x32x16_bf16 v[34:49], v[158:161], v[130:133], v[34:49]
	v_exp_f32_e32 v158, v100
	v_exp_f32_e32 v159, v101
	v_add_f32_e32 v65, v158, v65
	v_cvt_pk_bf16_f32 v99, v158, v159
	v_add_f32_e32 v65, v159, v65
	v_mfma_f32_32x32x16_bf16 v[66:81], v[154:157], v[134:137], v[66:81]
	v_exp_f32_e32 v154, v102
	v_exp_f32_e32 v155, v103
	v_add_f32_e32 v65, v154, v65
	v_cvt_pk_bf16_f32 v100, v154, v155
	v_add_f32_e32 v65, v155, v65
	s_waitcnt lgkmcnt(3)
	v_mfma_f32_32x32x16_bf16 v[66:81], v[126:129], v[138:141], v[66:81]
	v_exp_f32_e32 v104, v104
	v_exp_f32_e32 v105, v105
	v_add_f32_e32 v65, v104, v65
	v_cvt_pk_bf16_f32 v101, v104, v105
	v_add_f32_e32 v65, v105, v65
	s_waitcnt lgkmcnt(2)
	v_mfma_f32_32x32x16_bf16 v[66:81], v[122:125], v[142:145], v[66:81]
	v_exp_f32_e32 v106, v106
	v_exp_f32_e32 v107, v107
	s_nop 0
	v_cvt_pk_bf16_f32 v102, v106, v107
	v_exp_f32_e32 v108, v108
	v_mfma_f32_32x32x16_bf16 v[34:49], v[60:63], v[134:137], v[34:49]
	v_exp_f32_e32 v109, v109
	v_add_f32_e32 v60, v106, v65
	v_add_f32_e32 v60, v107, v60
	v_add_f32_e32 v60, v108, v60
	v_cvt_pk_bf16_f32 v103, v108, v109
	v_exp_f32_e32 v110, v110
	v_exp_f32_e32 v111, v111
	s_waitcnt lgkmcnt(1)
	v_mfma_f32_32x32x16_bf16 v[34:49], v[56:59], v[138:141], v[34:49]
	v_add_f32_e32 v60, v109, v60
	v_add_f32_e32 v60, v110, v60
	v_cvt_pk_bf16_f32 v104, v110, v111
	v_exp_f32_e32 v112, v112
	v_exp_f32_e32 v162, v113
	v_add_f32_e32 v60, v111, v60
	v_add_f32_e32 v65, v112, v60
	v_cvt_pk_bf16_f32 v105, v112, v162
	s_setprio 0
	ds_read_b128 v[56:59], v64 offset:27648
	ds_read_b128 v[60:63], v64 offset:27680
	ds_read_b128 v[106:109], v64 offset:27712
	ds_read_b128 v[110:113], v64 offset:27744
	ds_read_b128 v[122:125], v64 offset:32256
	ds_read_b128 v[126:129], v64 offset:32288
	ds_read_b128 v[154:157], v64 offset:32320
	ds_read_b128 v[158:161], v64 offset:32352
	v_add_f32_e32 v64, v162, v65
	v_exp_f32_e32 v65, v82
	v_exp_f32_e32 v82, v83
	v_exp_f32_e32 v83, v84
	v_exp_f32_e32 v84, v85
	v_add_f32_e32 v64, v65, v64
	v_exp_f32_e32 v85, v86
	v_add_f32_e32 v64, v82, v64
	v_exp_f32_e32 v86, v87
	v_add_f32_e32 v64, v83, v64
	v_exp_f32_e32 v87, v88
	v_add_f32_e32 v64, v84, v64
	v_exp_f32_e32 v88, v89
	v_add_f32_e32 v64, v85, v64
	v_exp_f32_e32 v89, v90
	v_add_f32_e32 v64, v86, v64
	v_exp_f32_e32 v90, v91
	v_add_f32_e32 v64, v87, v64
	v_exp_f32_e32 v91, v92
	v_add_f32_e32 v64, v88, v64
	v_exp_f32_e32 v92, v93
	v_add_f32_e32 v64, v89, v64
	v_exp_f32_e32 v93, v94
	v_add_f32_e32 v64, v90, v64
	v_exp_f32_e32 v94, v95
	v_add_f32_e32 v64, v91, v64
	v_exp_f32_e32 v95, v96
	v_add_f32_e32 v64, v92, v64
	v_exp_f32_e32 v96, v97
	v_add_f32_e32 v64, v93, v64
	v_add_f32_e32 v64, v94, v64
	v_add_f32_e32 v64, v95, v64
	v_add_f32_e32 v64, v96, v64
	v_cvt_pk_bf16_f32 v82, v65, v82
	v_cvt_pk_bf16_f32 v83, v83, v84
	v_cvt_pk_bf16_f32 v84, v85, v86
	v_cvt_pk_bf16_f32 v85, v87, v88
	v_cvt_pk_bf16_f32 v86, v89, v90
	v_cvt_pk_bf16_f32 v87, v91, v92
	v_cvt_pk_bf16_f32 v88, v93, v94
	v_cvt_pk_bf16_f32 v89, v95, v96
	s_setprio 1
	s_waitcnt lgkmcnt(7)
	v_mfma_f32_32x32x16_bf16 v[18:33], v[56:59], v[98:101], v[18:33]
	v_add_f32_e32 v210, v50, v64
	s_waitcnt lgkmcnt(3)
	v_mfma_f32_32x32x16_bf16 v[2:17], v[122:125], v[98:101], v[2:17]
	v_mfma_f32_32x32x16_bf16 v[18:33], v[60:63], v[102:105], v[18:33]
	s_waitcnt lgkmcnt(2)
	v_mfma_f32_32x32x16_bf16 v[2:17], v[126:129], v[102:105], v[2:17]
	v_mfma_f32_32x32x16_bf16 v[18:33], v[106:109], v[82:85], v[18:33]
	s_waitcnt lgkmcnt(1)
	v_mfma_f32_32x32x16_bf16 v[2:17], v[154:157], v[82:85], v[2:17]
	v_mfma_f32_32x32x16_bf16 v[18:33], v[110:113], v[86:89], v[18:33]
	s_waitcnt lgkmcnt(0)
	v_mfma_f32_32x32x16_bf16 v[2:17], v[158:161], v[86:89], v[2:17]
	v_mfma_f32_32x32x16_bf16 v[34:49], v[52:55], v[142:145], v[34:49]
	s_setprio 0
	s_movk_i32 s2, 0x4800
	s_mov_b32 s3, 0
	s_mov_b32 s0, 0x9000
	s_mov_b32 s10, 6
	v_mov_b32_e32 v50, v51
	v_mov_b32_e32 v52, v51
	v_mov_b32_e32 v53, v51
	v_mov_b32_e32 v54, v51
	v_mov_b32_e32 v55, v51
	v_mov_b32_e32 v56, v51
	v_mov_b32_e32 v57, v51
	v_mov_b32_e32 v58, v51
	v_mov_b32_e32 v59, v51
	v_mov_b32_e32 v60, v51
	v_mov_b32_e32 v61, v51
	v_mov_b32_e32 v62, v51
	v_mov_b32_e32 v63, v51
	v_mov_b32_e32 v64, v51
	v_mov_b32_e32 v65, v51
	s_waitcnt vmcnt(3)
	ds_write_b128 v169, v[114:117]
	s_waitcnt vmcnt(2)
	ds_write_b128 v170, v[118:121] offset:9216
	v_readlane_b32 s1, v255, 20
	s_nop 3
	s_cmp_lt_u32 s1, 0x42400000
	s_cbranch_scc0 .Lattn_online_pre
	v_sub_f32_e32 v50, s1, v206
	v_exp_f32_e64 v52, -v50
	v_mov_b32_e32 v206, s1
	v_readfirstlane_b32 s3, v194
	v_readfirstlane_b32 s12, v195
	v_readfirstlane_b32 s15, v208
	v_readfirstlane_b32 s23, v209
	v_add_u32_e32 v248, 0x2400, v0
	v_pk_add_f32 v[66:67], v[66:67], v[50:51] op_sel_hi:[1,0] neg_lo:[0,1] neg_hi:[0,1]
	v_pk_add_f32 v[68:69], v[68:69], v[50:51] op_sel_hi:[1,0] neg_lo:[0,1] neg_hi:[0,1]
	v_pk_add_f32 v[70:71], v[70:71], v[50:51] op_sel_hi:[1,0] neg_lo:[0,1] neg_hi:[0,1]
	v_pk_add_f32 v[72:73], v[72:73], v[50:51] op_sel_hi:[1,0] neg_lo:[0,1] neg_hi:[0,1]
	v_pk_add_f32 v[74:75], v[74:75], v[50:51] op_sel_hi:[1,0] neg_lo:[0,1] neg_hi:[0,1]
	v_pk_add_f32 v[76:77], v[76:77], v[50:51] op_sel_hi:[1,0] neg_lo:[0,1] neg_hi:[0,1]
	v_pk_add_f32 v[78:79], v[78:79], v[50:51] op_sel_hi:[1,0] neg_lo:[0,1] neg_hi:[0,1]
	v_pk_add_f32 v[80:81], v[80:81], v[50:51] op_sel_hi:[1,0] neg_lo:[0,1] neg_hi:[0,1]
	v_pk_add_f32 v[34:35], v[34:35], v[50:51] op_sel_hi:[1,0] neg_lo:[0,1] neg_hi:[0,1]
	v_pk_add_f32 v[36:37], v[36:37], v[50:51] op_sel_hi:[1,0] neg_lo:[0,1] neg_hi:[0,1]
	v_pk_add_f32 v[38:39], v[38:39], v[50:51] op_sel_hi:[1,0] neg_lo:[0,1] neg_hi:[0,1]
	v_pk_add_f32 v[40:41], v[40:41], v[50:51] op_sel_hi:[1,0] neg_lo:[0,1] neg_hi:[0,1]
	v_pk_add_f32 v[42:43], v[42:43], v[50:51] op_sel_hi:[1,0] neg_lo:[0,1] neg_hi:[0,1]
	v_pk_add_f32 v[44:45], v[44:45], v[50:51] op_sel_hi:[1,0] neg_lo:[0,1] neg_hi:[0,1]
	v_pk_add_f32 v[46:47], v[46:47], v[50:51] op_sel_hi:[1,0] neg_lo:[0,1] neg_hi:[0,1]
	v_pk_add_f32 v[48:49], v[48:49], v[50:51] op_sel_hi:[1,0] neg_lo:[0,1] neg_hi:[0,1]
	v_subrev_u32_e32 v252, s3, v194
	v_subrev_u32_e32 v253, s15, v208
	v_pk_mul_f32 v[2:3], v[2:3], v[52:53] op_sel_hi:[1,0]
	v_pk_mul_f32 v[4:5], v[4:5], v[52:53] op_sel_hi:[1,0]
	v_pk_mul_f32 v[6:7], v[6:7], v[52:53] op_sel_hi:[1,0]
	v_pk_mul_f32 v[8:9], v[8:9], v[52:53] op_sel_hi:[1,0]
	v_pk_mul_f32 v[10:11], v[10:11], v[52:53] op_sel_hi:[1,0]
	v_pk_mul_f32 v[12:13], v[12:13], v[52:53] op_sel_hi:[1,0]
	v_pk_mul_f32 v[14:15], v[14:15], v[52:53] op_sel_hi:[1,0]
	v_pk_mul_f32 v[16:17], v[16:17], v[52:53] op_sel_hi:[1,0]
	v_pk_mul_f32 v[18:19], v[18:19], v[52:53] op_sel_hi:[1,0]
	v_pk_mul_f32 v[20:21], v[20:21], v[52:53] op_sel_hi:[1,0]
	v_pk_mul_f32 v[22:23], v[22:23], v[52:53] op_sel_hi:[1,0]
	v_pk_mul_f32 v[24:25], v[24:25], v[52:53] op_sel_hi:[1,0]
	v_pk_mul_f32 v[26:27], v[26:27], v[52:53] op_sel_hi:[1,0]
	v_pk_mul_f32 v[28:29], v[28:29], v[52:53] op_sel_hi:[1,0]
	v_pk_mul_f32 v[30:31], v[30:31], v[52:53] op_sel_hi:[1,0]
	v_pk_mul_f32 v[32:33], v[32:33], v[52:53] op_sel_hi:[1,0]
	v_mul_f32_e32 v210, v210, v52
	v_xor_b32_e32 v50, 0x80000000, v206
	v_mov_b32_e32 v51, v50
	v_mov_b32_e32 v52, v50
	v_mov_b32_e32 v53, v50
	v_mov_b32_e32 v54, v50
	v_mov_b32_e32 v55, v50
	v_mov_b32_e32 v56, v50
	v_mov_b32_e32 v57, v50
	v_mov_b32_e32 v58, v50
	v_mov_b32_e32 v59, v50
	v_mov_b32_e32 v60, v50
	v_mov_b32_e32 v61, v50
	v_mov_b32_e32 v62, v50
	v_mov_b32_e32 v63, v50
	v_mov_b32_e32 v64, v50
	v_mov_b32_e32 v65, v50
.Lattn_fx_top:
	s_add_i32 s11, s10, -1
	s_min_i32 s1, s11, s58
	s_mul_i32 s44, s1, 0xa0000
	s_add_u32 s44, s3, s44
	s_addc_u32 s45, s12, 0
	s_lshl_b32 s46, s1, 7
	s_add_u32 s46, s15, s46
	s_addc_u32 s47, s23, 0
	s_add_i32 s24, s10, -2
	s_cmp_lt_u32 s24, s16
	s_cselect_b64 s[0:1], -1, 0
	s_waitcnt lgkmcnt(0)
	s_barrier
	ds_read_b128 v[162:165], v193
	ds_read_b128 v[178:181], v193 offset:4608
	ds_read_b128 v[166:169], v193 offset:32
	ds_read_b128 v[182:185], v193 offset:4640
	ds_read_b128 v[170:173], v193 offset:64
	ds_read_b128 v[186:189], v193 offset:4672
	ds_read_b128 v[174:177], v193 offset:96
	ds_read_b128 v[82:85], v193 offset:4704
	global_load_dwordx4 v[154:157], v252, s[44:45] offset:1024
	global_load_dwordx4 v[158:161], v253, s[46:47]
	v_exp_f32_e32 v66, v66
	v_exp_f32_e32 v67, v67
	v_exp_f32_e32 v68, v68
	v_exp_f32_e32 v69, v69
	v_add_f32_e32 v246, v66, v67
	v_cvt_pk_bf16_f32 v66, v66, v67
	s_waitcnt lgkmcnt(7)
	v_mfma_f32_32x32x16_bf16 v[114:129], v[162:165], v[130:133], v[50:65]
	ds_read_b128 v[86:89], v248 offset:36864
	ds_read_b128 v[216:219], v248 offset:41472
	v_exp_f32_e32 v70, v70
	v_exp_f32_e32 v71, v71
	v_add_f32_e32 v246, v68, v246
	v_add_f32_e32 v246, v69, v246
	v_cvt_pk_bf16_f32 v67, v68, v69
	s_waitcnt lgkmcnt(8)
	v_mfma_f32_32x32x16_bf16 v[98:113], v[178:181], v[130:133], v[50:65]
	ds_read_b128 v[90:93], v248 offset:36896
	ds_read_b128 v[220:223], v248 offset:41504
	v_exp_f32_e32 v72, v72
	v_exp_f32_e32 v73, v73
	v_add_f32_e32 v246, v70, v246
	v_add_f32_e32 v246, v71, v246
	v_cvt_pk_bf16_f32 v68, v70, v71
	s_waitcnt lgkmcnt(9)
	v_mfma_f32_32x32x16_bf16 v[114:129], v[166:169], v[134:137], v[114:129]
	ds_read_b128 v[94:97], v248 offset:36928
	ds_read_b128 v[224:227], v248 offset:41536
	v_exp_f32_e32 v74, v74
	v_exp_f32_e32 v75, v75
	v_add_f32_e32 v246, v72, v246
	v_add_f32_e32 v246, v73, v246
	v_cvt_pk_bf16_f32 v69, v72, v73
	s_waitcnt lgkmcnt(10)
	v_mfma_f32_32x32x16_bf16 v[98:113], v[182:185], v[134:137], v[98:113]
	ds_read_b128 v[212:215], v248 offset:36960
	ds_read_b128 v[242:245], v248 offset:41568
	v_exp_f32_e32 v76, v76
	v_exp_f32_e32 v77, v77
	v_add_f32_e32 v246, v74, v246
	v_add_f32_e32 v246, v75, v246
	v_cvt_pk_bf16_f32 v70, v74, v75
	s_waitcnt lgkmcnt(11)
	v_mfma_f32_32x32x16_bf16 v[114:129], v[170:173], v[138:141], v[114:129]
	v_exp_f32_e32 v78, v78
	v_exp_f32_e32 v79, v79
	v_add_f32_e32 v246, v76, v246
	v_add_f32_e32 v246, v77, v246
	v_cvt_pk_bf16_f32 v71, v76, v77
	s_waitcnt lgkmcnt(10)
	v_mfma_f32_32x32x16_bf16 v[98:113], v[186:189], v[138:141], v[98:113]
	v_exp_f32_e32 v80, v80
	v_exp_f32_e32 v81, v81
	v_add_f32_e32 v246, v78, v246
	v_add_f32_e32 v246, v79, v246
	v_cvt_pk_bf16_f32 v72, v78, v79
	s_waitcnt lgkmcnt(9)
	v_mfma_f32_32x32x16_bf16 v[114:129], v[174:177], v[142:145], v[114:129]
	v_exp_f32_e32 v34, v34
	v_exp_f32_e32 v35, v35
	v_add_f32_e32 v246, v80, v246
	v_add_f32_e32 v246, v81, v246
	v_cvt_pk_bf16_f32 v73, v80, v81
	s_waitcnt lgkmcnt(8)
	v_mfma_f32_32x32x16_bf16 v[98:113], v[82:85], v[142:145], v[98:113]
	v_exp_f32_e32 v36, v36
	v_exp_f32_e32 v37, v37
	v_add_f32_e32 v247, v34, v35
	v_cvt_pk_bf16_f32 v74, v34, v35
	s_waitcnt lgkmcnt(7)
	v_mfma_f32_32x32x16_bf16 v[18:33], v[86:89], v[66:69], v[18:33]
	v_exp_f32_e32 v38, v38
	v_exp_f32_e32 v39, v39
	v_add_f32_e32 v247, v36, v247
	v_add_f32_e32 v247, v37, v247
	v_cvt_pk_bf16_f32 v75, v36, v37
	s_waitcnt lgkmcnt(6)
	v_mfma_f32_32x32x16_bf16 v[2:17], v[216:219], v[66:69], v[2:17]
	v_exp_f32_e32 v40, v40
	v_exp_f32_e32 v41, v41
	v_add_f32_e32 v247, v38, v247
	v_add_f32_e32 v247, v39, v247
	v_cvt_pk_bf16_f32 v76, v38, v39
	s_waitcnt lgkmcnt(5)
	v_mfma_f32_32x32x16_bf16 v[18:33], v[90:93], v[70:73], v[18:33]
	v_exp_f32_e32 v42, v42
	v_exp_f32_e32 v43, v43
	v_add_f32_e32 v247, v40, v247
	v_add_f32_e32 v247, v41, v247
	v_cvt_pk_bf16_f32 v77, v40, v41
	s_waitcnt lgkmcnt(4)
	v_mfma_f32_32x32x16_bf16 v[2:17], v[220:223], v[70:73], v[2:17]
	v_exp_f32_e32 v44, v44
	v_exp_f32_e32 v45, v45
	v_add_f32_e32 v247, v42, v247
	v_add_f32_e32 v247, v43, v247
	v_cvt_pk_bf16_f32 v78, v42, v43
	s_waitcnt lgkmcnt(3)
	v_mfma_f32_32x32x16_bf16 v[18:33], v[94:97], v[74:77], v[18:33]
	v_exp_f32_e32 v46, v46
	v_exp_f32_e32 v47, v47
	v_add_f32_e32 v247, v44, v247
	v_add_f32_e32 v247, v45, v247
	v_cvt_pk_bf16_f32 v79, v44, v45
	s_waitcnt lgkmcnt(2)
	v_mfma_f32_32x32x16_bf16 v[2:17], v[224:227], v[74:77], v[2:17]
	v_exp_f32_e32 v48, v48
	v_exp_f32_e32 v49, v49
	v_add_f32_e32 v247, v46, v247
	v_add_f32_e32 v247, v47, v247
	v_cvt_pk_bf16_f32 v80, v46, v47
	v_cvt_pk_bf16_f32 v81, v48, v49
	v_add_f32_e32 v247, v48, v247
	v_add_f32_e32 v247, v49, v247
	s_waitcnt lgkmcnt(1)
	v_mfma_f32_32x32x16_bf16 v[18:33], v[212:215], v[78:81], v[18:33]
	s_waitcnt lgkmcnt(0)
	v_mfma_f32_32x32x16_bf16 v[2:17], v[242:245], v[78:81], v[2:17]
	v_add_f32_e32 v210, v210, v246
	v_add_f32_e32 v210, v210, v247
	s_cmp_ge_u32 s24, s16
	s_cbranch_scc1 .Lattn_fx_skipw1
	s_waitcnt vmcnt(3)
	ds_write_b128 v192, v[146:149] offset:18432
	s_waitcnt vmcnt(2)
	ds_write_b128 v204, v[150:153] offset:27648
.Lattn_fx_skipw1:
	s_min_i32 s24, s10, s58
	s_mul_i32 s44, s24, 0xa0000
	s_add_u32 s44, s3, s44
	s_addc_u32 s45, s12, 0
	s_lshl_b32 s46, s24, 7
	s_add_u32 s46, s15, s46
	s_addc_u32 s47, s23, 0
	s_waitcnt lgkmcnt(0)
	s_barrier
	ds_read_b128 v[162:165], v193 offset:18432
	ds_read_b128 v[178:181], v193 offset:23040
	ds_read_b128 v[166:169], v193 offset:18464
	ds_read_b128 v[182:185], v193 offset:23072
	ds_read_b128 v[170:173], v193 offset:18496
	ds_read_b128 v[186:189], v193 offset:23104
	ds_read_b128 v[174:177], v193 offset:18528
	ds_read_b128 v[82:85], v193 offset:23136
	global_load_dwordx4 v[146:149], v252, s[44:45] offset:1024
	global_load_dwordx4 v[150:153], v253, s[46:47]
	v_exp_f32_e32 v114, v114
	v_exp_f32_e32 v115, v115
	v_exp_f32_e32 v116, v116
	v_exp_f32_e32 v117, v117
	v_add_f32_e32 v246, v114, v115
	v_cvt_pk_bf16_f32 v114, v114, v115
	s_waitcnt lgkmcnt(7)
	v_mfma_f32_32x32x16_bf16 v[66:81], v[162:165], v[130:133], v[50:65]
	ds_read_b128 v[86:89], v248
	ds_read_b128 v[216:219], v248 offset:4608
	v_exp_f32_e32 v118, v118
	v_exp_f32_e32 v119, v119
	v_add_f32_e32 v246, v116, v246
	v_add_f32_e32 v246, v117, v246
	v_cvt_pk_bf16_f32 v115, v116, v117
	s_waitcnt lgkmcnt(8)
	v_mfma_f32_32x32x16_bf16 v[34:49], v[178:181], v[130:133], v[50:65]
	ds_read_b128 v[90:93], v248 offset:32
	ds_read_b128 v[220:223], v248 offset:4640
	v_exp_f32_e32 v120, v120
	v_exp_f32_e32 v121, v121
	v_add_f32_e32 v246, v118, v246
	v_add_f32_e32 v246, v119, v246
	v_cvt_pk_bf16_f32 v116, v118, v119
	s_waitcnt lgkmcnt(9)
	v_mfma_f32_32x32x16_bf16 v[66:81], v[166:169], v[134:137], v[66:81]
	ds_read_b128 v[94:97], v248 offset:64
	ds_read_b128 v[224:227], v248 offset:4672
	v_exp_f32_e32 v122, v122
	v_exp_f32_e32 v123, v123
	v_add_f32_e32 v246, v120, v246
	v_add_f32_e32 v246, v121, v246
	v_cvt_pk_bf16_f32 v117, v120, v121
	s_waitcnt lgkmcnt(10)
	v_mfma_f32_32x32x16_bf16 v[34:49], v[182:185], v[134:137], v[34:49]
	ds_read_b128 v[212:215], v248 offset:96
	ds_read_b128 v[242:245], v248 offset:4704
	v_exp_f32_e32 v124, v124
	v_exp_f32_e32 v125, v125
	v_add_f32_e32 v246, v122, v246
	v_add_f32_e32 v246, v123, v246
	v_cvt_pk_bf16_f32 v118, v122, v123
	s_waitcnt lgkmcnt(11)
	v_mfma_f32_32x32x16_bf16 v[66:81], v[170:173], v[138:141], v[66:81]
	v_exp_f32_e32 v126, v126
	v_exp_f32_e32 v127, v127
	v_add_f32_e32 v246, v124, v246
	v_add_f32_e32 v246, v125, v246
	v_cvt_pk_bf16_f32 v119, v124, v125
	s_waitcnt lgkmcnt(10)
	v_mfma_f32_32x32x16_bf16 v[34:49], v[186:189], v[138:141], v[34:49]
	v_exp_f32_e32 v128, v128
	v_exp_f32_e32 v129, v129
	v_add_f32_e32 v246, v126, v246
	v_add_f32_e32 v246, v127, v246
	v_cvt_pk_bf16_f32 v120, v126, v127
	s_waitcnt lgkmcnt(9)
	v_mfma_f32_32x32x16_bf16 v[66:81], v[174:177], v[142:145], v[66:81]
	v_exp_f32_e32 v98, v98
	v_exp_f32_e32 v99, v99
	v_add_f32_e32 v246, v128, v246
	v_add_f32_e32 v246, v129, v246
	v_cvt_pk_bf16_f32 v121, v128, v129
	s_waitcnt lgkmcnt(8)
	v_mfma_f32_32x32x16_bf16 v[34:49], v[82:85], v[142:145], v[34:49]
	v_exp_f32_e32 v100, v100
	v_exp_f32_e32 v101, v101
	v_add_f32_e32 v247, v98, v99
	v_cvt_pk_bf16_f32 v122, v98, v99
	s_waitcnt lgkmcnt(7)
	v_mfma_f32_32x32x16_bf16 v[18:33], v[86:89], v[114:117], v[18:33]
	v_exp_f32_e32 v102, v102
	v_exp_f32_e32 v103, v103
	v_add_f32_e32 v247, v100, v247
	v_add_f32_e32 v247, v101, v247
	v_cvt_pk_bf16_f32 v123, v100, v101
	s_waitcnt lgkmcnt(6)
	v_mfma_f32_32x32x16_bf16 v[2:17], v[216:219], v[114:117], v[2:17]
	v_exp_f32_e32 v104, v104
	v_exp_f32_e32 v105, v105
	v_add_f32_e32 v247, v102, v247
	v_add_f32_e32 v247, v103, v247
	v_cvt_pk_bf16_f32 v124, v102, v103
	s_waitcnt lgkmcnt(5)
	v_mfma_f32_32x32x16_bf16 v[18:33], v[90:93], v[118:121], v[18:33]
	v_exp_f32_e32 v106, v106
	v_exp_f32_e32 v107, v107
	v_add_f32_e32 v247, v104, v247
	v_add_f32_e32 v247, v105, v247
	v_cvt_pk_bf16_f32 v125, v104, v105
	s_waitcnt lgkmcnt(4)
	v_mfma_f32_32x32x16_bf16 v[2:17], v[220:223], v[118:121], v[2:17]
	v_exp_f32_e32 v108, v108
	v_exp_f32_e32 v109, v109
	v_add_f32_e32 v247, v106, v247
	v_add_f32_e32 v247, v107, v247
	v_cvt_pk_bf16_f32 v126, v106, v107
	s_waitcnt lgkmcnt(3)
	v_mfma_f32_32x32x16_bf16 v[18:33], v[94:97], v[122:125], v[18:33]
	v_exp_f32_e32 v110, v110
	v_exp_f32_e32 v111, v111
	v_add_f32_e32 v247, v108, v247
	v_add_f32_e32 v247, v109, v247
	v_cvt_pk_bf16_f32 v127, v108, v109
	s_waitcnt lgkmcnt(2)
	v_mfma_f32_32x32x16_bf16 v[2:17], v[224:227], v[122:125], v[2:17]
	v_exp_f32_e32 v112, v112
	v_exp_f32_e32 v113, v113
	v_add_f32_e32 v247, v110, v247
	v_add_f32_e32 v247, v111, v247
	v_cvt_pk_bf16_f32 v128, v110, v111
	v_cvt_pk_bf16_f32 v129, v112, v113
	v_add_f32_e32 v247, v112, v247
	v_add_f32_e32 v247, v113, v247
	s_waitcnt lgkmcnt(1)
	v_mfma_f32_32x32x16_bf16 v[18:33], v[212:215], v[126:129], v[18:33]
	s_waitcnt lgkmcnt(0)
	v_mfma_f32_32x32x16_bf16 v[2:17], v[242:245], v[126:129], v[2:17]
	v_add_f32_e32 v210, v210, v246
	v_add_f32_e32 v210, v210, v247
	s_cmp_ge_u32 s11, s16
	s_cbranch_scc1 .Lattn_fx_skipw2
	s_waitcnt vmcnt(3)
	ds_write_b128 v192, v[154:157] offset:55296
	s_waitcnt vmcnt(2)
	ds_write_b128 v204, v[158:161] offset:64512
.Lattn_fx_skipw2:
	s_add_i32 s10, s10, 2
	s_cmp_lt_u32 s11, s16
	s_cbranch_scc0 .Lattn_fx_exit0
	s_add_i32 s11, s10, -1
	s_min_i32 s1, s11, s58
	s_mul_i32 s44, s1, 0xa0000
	s_add_u32 s44, s3, s44
	s_addc_u32 s45, s12, 0
	s_lshl_b32 s46, s1, 7
	s_add_u32 s46, s15, s46
	s_addc_u32 s47, s23, 0
	s_add_i32 s24, s10, -2
	s_cmp_lt_u32 s24, s16
	s_cselect_b64 s[0:1], -1, 0
	s_waitcnt lgkmcnt(0)
	s_barrier
	ds_read_b128 v[162:165], v193 offset:55296
	ds_read_b128 v[178:181], v193 offset:59904
	ds_read_b128 v[166:169], v193 offset:55328
	ds_read_b128 v[182:185], v193 offset:59936
	ds_read_b128 v[170:173], v193 offset:55360
	ds_read_b128 v[186:189], v193 offset:59968
	ds_read_b128 v[174:177], v193 offset:55392
	ds_read_b128 v[82:85], v193 offset:60000
	global_load_dwordx4 v[154:157], v252, s[44:45] offset:1024
	global_load_dwordx4 v[158:161], v253, s[46:47]
	v_exp_f32_e32 v66, v66
	v_exp_f32_e32 v67, v67
	v_exp_f32_e32 v68, v68
	v_exp_f32_e32 v69, v69
	v_add_f32_e32 v246, v66, v67
	v_cvt_pk_bf16_f32 v66, v66, v67
	s_waitcnt lgkmcnt(7)
	v_mfma_f32_32x32x16_bf16 v[114:129], v[162:165], v[130:133], v[50:65]
	ds_read_b128 v[86:89], v248 offset:18432
	ds_read_b128 v[216:219], v248 offset:23040
	v_exp_f32_e32 v70, v70
	v_exp_f32_e32 v71, v71
	v_add_f32_e32 v246, v68, v246
	v_add_f32_e32 v246, v69, v246
	v_cvt_pk_bf16_f32 v67, v68, v69
	s_waitcnt lgkmcnt(8)
	v_mfma_f32_32x32x16_bf16 v[98:113], v[178:181], v[130:133], v[50:65]
	ds_read_b128 v[90:93], v248 offset:18464
	ds_read_b128 v[220:223], v248 offset:23072
	v_exp_f32_e32 v72, v72
	v_exp_f32_e32 v73, v73
	v_add_f32_e32 v246, v70, v246
	v_add_f32_e32 v246, v71, v246
	v_cvt_pk_bf16_f32 v68, v70, v71
	s_waitcnt lgkmcnt(9)
	v_mfma_f32_32x32x16_bf16 v[114:129], v[166:169], v[134:137], v[114:129]
	ds_read_b128 v[94:97], v248 offset:18496
	ds_read_b128 v[224:227], v248 offset:23104
	v_exp_f32_e32 v74, v74
	v_exp_f32_e32 v75, v75
	v_add_f32_e32 v246, v72, v246
	v_add_f32_e32 v246, v73, v246
	v_cvt_pk_bf16_f32 v69, v72, v73
	s_waitcnt lgkmcnt(10)
	v_mfma_f32_32x32x16_bf16 v[98:113], v[182:185], v[134:137], v[98:113]
	ds_read_b128 v[212:215], v248 offset:18528
	ds_read_b128 v[242:245], v248 offset:23136
	v_exp_f32_e32 v76, v76
	v_exp_f32_e32 v77, v77
	v_add_f32_e32 v246, v74, v246
	v_add_f32_e32 v246, v75, v246
	v_cvt_pk_bf16_f32 v70, v74, v75
	s_waitcnt lgkmcnt(11)
	v_mfma_f32_32x32x16_bf16 v[114:129], v[170:173], v[138:141], v[114:129]
	v_exp_f32_e32 v78, v78
	v_exp_f32_e32 v79, v79
	v_add_f32_e32 v246, v76, v246
	v_add_f32_e32 v246, v77, v246
	v_cvt_pk_bf16_f32 v71, v76, v77
	s_waitcnt lgkmcnt(10)
	v_mfma_f32_32x32x16_bf16 v[98:113], v[186:189], v[138:141], v[98:113]
	v_exp_f32_e32 v80, v80
	v_exp_f32_e32 v81, v81
	v_add_f32_e32 v246, v78, v246
	v_add_f32_e32 v246, v79, v246
	v_cvt_pk_bf16_f32 v72, v78, v79
	s_waitcnt lgkmcnt(9)
	v_mfma_f32_32x32x16_bf16 v[114:129], v[174:177], v[142:145], v[114:129]
	v_exp_f32_e32 v34, v34
	v_exp_f32_e32 v35, v35
	v_add_f32_e32 v246, v80, v246
	v_add_f32_e32 v246, v81, v246
	v_cvt_pk_bf16_f32 v73, v80, v81
	s_waitcnt lgkmcnt(8)
	v_mfma_f32_32x32x16_bf16 v[98:113], v[82:85], v[142:145], v[98:113]
	v_exp_f32_e32 v36, v36
	v_exp_f32_e32 v37, v37
	v_add_f32_e32 v247, v34, v35
	v_cvt_pk_bf16_f32 v74, v34, v35
	s_waitcnt lgkmcnt(7)
	v_mfma_f32_32x32x16_bf16 v[18:33], v[86:89], v[66:69], v[18:33]
	v_exp_f32_e32 v38, v38
	v_exp_f32_e32 v39, v39
	v_add_f32_e32 v247, v36, v247
	v_add_f32_e32 v247, v37, v247
	v_cvt_pk_bf16_f32 v75, v36, v37
	s_waitcnt lgkmcnt(6)
	v_mfma_f32_32x32x16_bf16 v[2:17], v[216:219], v[66:69], v[2:17]
	v_exp_f32_e32 v40, v40
	v_exp_f32_e32 v41, v41
	v_add_f32_e32 v247, v38, v247
	v_add_f32_e32 v247, v39, v247
	v_cvt_pk_bf16_f32 v76, v38, v39
	s_waitcnt lgkmcnt(5)
	v_mfma_f32_32x32x16_bf16 v[18:33], v[90:93], v[70:73], v[18:33]
	v_exp_f32_e32 v42, v42
	v_exp_f32_e32 v43, v43
	v_add_f32_e32 v247, v40, v247
	v_add_f32_e32 v247, v41, v247
	v_cvt_pk_bf16_f32 v77, v40, v41
	s_waitcnt lgkmcnt(4)
	v_mfma_f32_32x32x16_bf16 v[2:17], v[220:223], v[70:73], v[2:17]
	v_exp_f32_e32 v44, v44
	v_exp_f32_e32 v45, v45
	v_add_f32_e32 v247, v42, v247
	v_add_f32_e32 v247, v43, v247
	v_cvt_pk_bf16_f32 v78, v42, v43
	s_waitcnt lgkmcnt(3)
	v_mfma_f32_32x32x16_bf16 v[18:33], v[94:97], v[74:77], v[18:33]
	v_exp_f32_e32 v46, v46
	v_exp_f32_e32 v47, v47
	v_add_f32_e32 v247, v44, v247
	v_add_f32_e32 v247, v45, v247
	v_cvt_pk_bf16_f32 v79, v44, v45
	s_waitcnt lgkmcnt(2)
	v_mfma_f32_32x32x16_bf16 v[2:17], v[224:227], v[74:77], v[2:17]
	v_exp_f32_e32 v48, v48
	v_exp_f32_e32 v49, v49
	v_add_f32_e32 v247, v46, v247
	v_add_f32_e32 v247, v47, v247
	v_cvt_pk_bf16_f32 v80, v46, v47
	v_cvt_pk_bf16_f32 v81, v48, v49
	v_add_f32_e32 v247, v48, v247
	v_add_f32_e32 v247, v49, v247
	s_waitcnt lgkmcnt(1)
	v_mfma_f32_32x32x16_bf16 v[18:33], v[212:215], v[78:81], v[18:33]
	s_waitcnt lgkmcnt(0)
	v_mfma_f32_32x32x16_bf16 v[2:17], v[242:245], v[78:81], v[2:17]
	v_add_f32_e32 v210, v210, v246
	v_add_f32_e32 v210, v210, v247
	s_cmp_ge_u32 s24, s16
	s_cbranch_scc1 .Lattn_fx_skipw3
	s_waitcnt vmcnt(3)
	ds_write_b128 v192, v[146:149] offset:36864
	s_waitcnt vmcnt(2)
	ds_write_b128 v204, v[150:153] offset:46080
; template <int HD, int MODE> ...
;     ...
;     int t = t0;
;     for (; t + 1 < t1; t += 2) { ATT_STEP(sa0, sa1, sb0, sb1, t, kstB, vstB, kstA, vstA); ATT_STEP(sb0, sb1, sa0, sa1, t + 1, kstA, vstA, kstB, vstB); }
;     if (t < t1) ATT_STEP(sa0, sa1, sb0, sb1, t, kstB, vstB, kstA, vstA);
.Lattn_fx_skipw3:
	s_min_i32 s24, s10, s58
	s_mul_i32 s44, s24, 0xa0000
	s_add_u32 s44, s3, s44
	s_addc_u32 s45, s12, 0
	s_lshl_b32 s46, s24, 7
	s_add_u32 s46, s15, s46
	s_addc_u32 s47, s23, 0
	s_waitcnt lgkmcnt(0)
	s_barrier
	ds_read_b128 v[162:165], v193 offset:36864
	ds_read_b128 v[178:181], v193 offset:41472
	ds_read_b128 v[166:169], v193 offset:36896
	ds_read_b128 v[182:185], v193 offset:41504
	ds_read_b128 v[170:173], v193 offset:36928
	ds_read_b128 v[186:189], v193 offset:41536
	ds_read_b128 v[174:177], v193 offset:36960
	ds_read_b128 v[82:85], v193 offset:41568
	global_load_dwordx4 v[146:149], v252, s[44:45] offset:1024
	global_load_dwordx4 v[150:153], v253, s[46:47]
	v_exp_f32_e32 v114, v114
	v_exp_f32_e32 v115, v115
	v_exp_f32_e32 v116, v116
	v_exp_f32_e32 v117, v117
	v_add_f32_e32 v246, v114, v115
	v_cvt_pk_bf16_f32 v114, v114, v115
	s_waitcnt lgkmcnt(7)
	v_mfma_f32_32x32x16_bf16 v[66:81], v[162:165], v[130:133], v[50:65]
	ds_read_b128 v[86:89], v248 offset:55296
	ds_read_b128 v[216:219], v248 offset:59904
	v_exp_f32_e32 v118, v118
	v_exp_f32_e32 v119, v119
	v_add_f32_e32 v246, v116, v246
	v_add_f32_e32 v246, v117, v246
	v_cvt_pk_bf16_f32 v115, v116, v117
	s_waitcnt lgkmcnt(8)
	v_mfma_f32_32x32x16_bf16 v[34:49], v[178:181], v[130:133], v[50:65]
	ds_read_b128 v[90:93], v248 offset:55328
	ds_read_b128 v[220:223], v248 offset:59936
	v_exp_f32_e32 v120, v120
	v_exp_f32_e32 v121, v121
	v_add_f32_e32 v246, v118, v246
	v_add_f32_e32 v246, v119, v246
	v_cvt_pk_bf16_f32 v116, v118, v119
	s_waitcnt lgkmcnt(9)
	v_mfma_f32_32x32x16_bf16 v[66:81], v[166:169], v[134:137], v[66:81]
	ds_read_b128 v[94:97], v248 offset:55360
	ds_read_b128 v[224:227], v248 offset:59968
	v_exp_f32_e32 v122, v122
	v_exp_f32_e32 v123, v123
	v_add_f32_e32 v246, v120, v246
	v_add_f32_e32 v246, v121, v246
	v_cvt_pk_bf16_f32 v117, v120, v121
	s_waitcnt lgkmcnt(10)
	v_mfma_f32_32x32x16_bf16 v[34:49], v[182:185], v[134:137], v[34:49]
	ds_read_b128 v[212:215], v248 offset:55392
	ds_read_b128 v[242:245], v248 offset:60000
	v_exp_f32_e32 v124, v124
	v_exp_f32_e32 v125, v125
	v_add_f32_e32 v246, v122, v246
	v_add_f32_e32 v246, v123, v246
	v_cvt_pk_bf16_f32 v118, v122, v123
	s_waitcnt lgkmcnt(11)
	v_mfma_f32_32x32x16_bf16 v[66:81], v[170:173], v[138:141], v[66:81]
	v_exp_f32_e32 v126, v126
	v_exp_f32_e32 v127, v127
	v_add_f32_e32 v246, v124, v246
	v_add_f32_e32 v246, v125, v246
	v_cvt_pk_bf16_f32 v119, v124, v125
	s_waitcnt lgkmcnt(10)
	v_mfma_f32_32x32x16_bf16 v[34:49], v[186:189], v[138:141], v[34:49]
	v_exp_f32_e32 v128, v128
	v_exp_f32_e32 v129, v129
	v_add_f32_e32 v246, v126, v246
	v_add_f32_e32 v246, v127, v246
	v_cvt_pk_bf16_f32 v120, v126, v127
	s_waitcnt lgkmcnt(9)
	v_mfma_f32_32x32x16_bf16 v[66:81], v[174:177], v[142:145], v[66:81]
	v_exp_f32_e32 v98, v98
	v_exp_f32_e32 v99, v99
	v_add_f32_e32 v246, v128, v246
	v_add_f32_e32 v246, v129, v246
	v_cvt_pk_bf16_f32 v121, v128, v129
	s_waitcnt lgkmcnt(8)
	v_mfma_f32_32x32x16_bf16 v[34:49], v[82:85], v[142:145], v[34:49]
	v_exp_f32_e32 v100, v100
	v_exp_f32_e32 v101, v101
	v_add_f32_e32 v247, v98, v99
	v_cvt_pk_bf16_f32 v122, v98, v99
	s_waitcnt lgkmcnt(7)
	v_mfma_f32_32x32x16_bf16 v[18:33], v[86:89], v[114:117], v[18:33]
	v_exp_f32_e32 v102, v102
	v_exp_f32_e32 v103, v103
	v_add_f32_e32 v247, v100, v247
	v_add_f32_e32 v247, v101, v247
	v_cvt_pk_bf16_f32 v123, v100, v101
	s_waitcnt lgkmcnt(6)
	v_mfma_f32_32x32x16_bf16 v[2:17], v[216:219], v[114:117], v[2:17]
	v_exp_f32_e32 v104, v104
	v_exp_f32_e32 v105, v105
	v_add_f32_e32 v247, v102, v247
	v_add_f32_e32 v247, v103, v247
	v_cvt_pk_bf16_f32 v124, v102, v103
	s_waitcnt lgkmcnt(5)
	v_mfma_f32_32x32x16_bf16 v[18:33], v[90:93], v[118:121], v[18:33]
	v_exp_f32_e32 v106, v106
	v_exp_f32_e32 v107, v107
	v_add_f32_e32 v247, v104, v247
	v_add_f32_e32 v247, v105, v247
	v_cvt_pk_bf16_f32 v125, v104, v105
	s_waitcnt lgkmcnt(4)
	v_mfma_f32_32x32x16_bf16 v[2:17], v[220:223], v[118:121], v[2:17]
	v_exp_f32_e32 v108, v108
	v_exp_f32_e32 v109, v109
	v_add_f32_e32 v247, v106, v247
	v_add_f32_e32 v247, v107, v247
	v_cvt_pk_bf16_f32 v126, v106, v107
	s_waitcnt lgkmcnt(3)
	v_mfma_f32_32x32x16_bf16 v[18:33], v[94:97], v[122:125], v[18:33]
	v_exp_f32_e32 v110, v110
	v_exp_f32_e32 v111, v111
	v_add_f32_e32 v247, v108, v247
	v_add_f32_e32 v247, v109, v247
	v_cvt_pk_bf16_f32 v127, v108, v109
	s_waitcnt lgkmcnt(2)
	v_mfma_f32_32x32x16_bf16 v[2:17], v[224:227], v[122:125], v[2:17]
	v_exp_f32_e32 v112, v112
	v_exp_f32_e32 v113, v113
	v_add_f32_e32 v247, v110, v247
	v_add_f32_e32 v247, v111, v247
	v_cvt_pk_bf16_f32 v128, v110, v111
	v_cvt_pk_bf16_f32 v129, v112, v113
	v_add_f32_e32 v247, v112, v247
	v_add_f32_e32 v247, v113, v247
	s_waitcnt lgkmcnt(1)
	v_mfma_f32_32x32x16_bf16 v[18:33], v[212:215], v[126:129], v[18:33]
	s_waitcnt lgkmcnt(0)
	v_mfma_f32_32x32x16_bf16 v[2:17], v[242:245], v[126:129], v[2:17]
	v_add_f32_e32 v210, v210, v246
	v_add_f32_e32 v210, v210, v247
	s_cmp_ge_u32 s11, s16
	s_cbranch_scc1 .Lattn_fx_skipw4
	s_waitcnt vmcnt(3)
	ds_write_b128 v192, v[154:157]
	s_waitcnt vmcnt(2)
	ds_write_b128 v204, v[158:161] offset:9216
.Lattn_fx_skipw4:
	s_add_i32 s10, s10, 2
	s_cmp_lt_u32 s11, s16
	s_cbranch_scc0 .Lattn_fx_exit1
	s_branch .Lattn_fx_top
.Lattn_fx_exit0:
	s_movk_i32 s2, 0x4800
	s_branch .LBB0_508
.Lattn_fx_exit1:
	s_mov_b32 s2, 0x9000
	s_branch .LBB0_508
